# L2 residency in the proj GEMM: the 16 epilogue stores of the proj tile marked non-temporal so the 201 MB output stream does not evict weight/activation tiles (timing-only, re-test on the current base)
# baseline (speedup 1.0000x reference)
.LBB0_492:
	v_lshrrev_b32_e32 v160, 2, v213
	v_and_b32_e32 v161, 3, v213
	v_lshlrev_b32_e32 v162, 6, v161
	v_lshl_add_u32 v162, v160, 2, v162
	s_lshl_b32 s4, s65, 8
	s_add_i32 s4, s4, s47
	s_andn2_b64 vcc, exec, s[40:41]
	v_add_u32_e32 v149, s4, v160
	s_lshl_b32 s4, s53, 8
	s_or_b32 s4, s4, s48
	v_lshl_add_u32 v142, v161, 3, s4
	s_lshl_b32 s4, s58, 10
	s_add_i32 s4, s51, s4
	v_lshl_add_u32 v154, v144, 2, s4
	ds_read_b32 v164, v154
	ds_read_b32 v166, v154 offset:64
	ds_read_b32 v168, v154 offset:128
	ds_read_b32 v170, v154 offset:192
	ds_read_b32 v172, v154 offset:512
	ds_read_b32 v174, v154 offset:576
	ds_read_b32 v176, v154 offset:640
	ds_read_b32 v178, v154 offset:704
	v_ashrrev_i32_e32 v143, 31, v142
	v_mov_b64_e32 v[140:141], s[16:17]
	v_lshlrev_b64 v[142:143], 1, v[142:143]
	s_mov_b64 s[30:31], -1
	s_waitcnt lgkmcnt(0)
	v_pk_mul_f32 v[126:127], v[126:127], v[164:165] op_sel_hi:[1,0]
	v_pk_mul_f32 v[128:129], v[128:129], v[164:165] op_sel_hi:[1,0]
	v_pk_mul_f32 v[122:123], v[122:123], v[164:165] op_sel_hi:[1,0]
	v_pk_mul_f32 v[124:125], v[124:125], v[164:165] op_sel_hi:[1,0]
	v_cvt_pk_bf16_f32 v180, v126, v127
	v_cvt_pk_bf16_f32 v181, v128, v129
	v_cvt_pk_bf16_f32 v182, v122, v123
	v_cvt_pk_bf16_f32 v183, v124, v125
	v_pk_mul_f32 v[114:115], v[114:115], v[164:165] op_sel_hi:[1,0]
	v_pk_mul_f32 v[116:117], v[116:117], v[164:165] op_sel_hi:[1,0]
	v_pk_mul_f32 v[106:107], v[106:107], v[164:165] op_sel_hi:[1,0]
	v_pk_mul_f32 v[108:109], v[108:109], v[164:165] op_sel_hi:[1,0]
	v_cvt_pk_bf16_f32 v184, v114, v115
	v_cvt_pk_bf16_f32 v185, v116, v117
	v_cvt_pk_bf16_f32 v186, v106, v107
	v_cvt_pk_bf16_f32 v187, v108, v109
	ds_bpermute_b32 v180, v162, v180
	ds_bpermute_b32 v181, v162, v181
	ds_bpermute_b32 v182, v162, v182
	ds_bpermute_b32 v183, v162, v183
	ds_bpermute_b32 v184, v162, v184
	ds_bpermute_b32 v185, v162, v185
	ds_bpermute_b32 v186, v162, v186
	ds_bpermute_b32 v187, v162, v187
	v_mad_i64_i32 v[196:197], s[4:5], v149, s11, v[140:141]
	v_lshl_add_u64 v[196:197], v[196:197], 0, v[142:143]
	v_pk_mul_f32 v[118:119], v[118:119], v[166:167] op_sel_hi:[1,0]
	v_pk_mul_f32 v[120:121], v[120:121], v[166:167] op_sel_hi:[1,0]
	v_pk_mul_f32 v[110:111], v[110:111], v[166:167] op_sel_hi:[1,0]
	v_pk_mul_f32 v[112:113], v[112:113], v[166:167] op_sel_hi:[1,0]
	v_cvt_pk_bf16_f32 v188, v118, v119
	v_cvt_pk_bf16_f32 v189, v120, v121
	v_cvt_pk_bf16_f32 v190, v110, v111
	v_cvt_pk_bf16_f32 v191, v112, v113
	v_pk_mul_f32 v[98:99], v[98:99], v[166:167] op_sel_hi:[1,0]
	v_pk_mul_f32 v[100:101], v[100:101], v[166:167] op_sel_hi:[1,0]
	v_pk_mul_f32 v[90:91], v[90:91], v[166:167] op_sel_hi:[1,0]
	v_pk_mul_f32 v[92:93], v[92:93], v[166:167] op_sel_hi:[1,0]
	v_cvt_pk_bf16_f32 v192, v98, v99
	v_cvt_pk_bf16_f32 v193, v100, v101
	v_cvt_pk_bf16_f32 v194, v90, v91
	v_cvt_pk_bf16_f32 v195, v92, v93
	ds_bpermute_b32 v188, v162, v188
	ds_bpermute_b32 v189, v162, v189
	ds_bpermute_b32 v190, v162, v190
	ds_bpermute_b32 v191, v162, v191
	ds_bpermute_b32 v192, v162, v192
	ds_bpermute_b32 v193, v162, v193
	ds_bpermute_b32 v194, v162, v194
	ds_bpermute_b32 v195, v162, v195
	v_add_u32_e32 v200, 16, v149
	v_mad_i64_i32 v[198:199], s[4:5], v200, s11, v[140:141]
	v_lshl_add_u64 v[198:199], v[198:199], 0, v[142:143]
	s_waitcnt lgkmcnt(8)
	global_store_dwordx4 v[196:197], v[180:183], off nt
	global_store_dwordx4 v[196:197], v[184:187], off offset:256 nt
	v_pk_mul_f32 v[102:103], v[102:103], v[168:169] op_sel_hi:[1,0]
	v_pk_mul_f32 v[104:105], v[104:105], v[168:169] op_sel_hi:[1,0]
	v_pk_mul_f32 v[94:95], v[94:95], v[168:169] op_sel_hi:[1,0]
	v_pk_mul_f32 v[96:97], v[96:97], v[168:169] op_sel_hi:[1,0]
	v_cvt_pk_bf16_f32 v180, v102, v103
	v_cvt_pk_bf16_f32 v181, v104, v105
	v_cvt_pk_bf16_f32 v182, v94, v95
	v_cvt_pk_bf16_f32 v183, v96, v97
	v_pk_mul_f32 v[82:83], v[82:83], v[168:169] op_sel_hi:[1,0]
	v_pk_mul_f32 v[84:85], v[84:85], v[168:169] op_sel_hi:[1,0]
	v_pk_mul_f32 v[74:75], v[74:75], v[168:169] op_sel_hi:[1,0]
	v_pk_mul_f32 v[76:77], v[76:77], v[168:169] op_sel_hi:[1,0]
	v_cvt_pk_bf16_f32 v184, v82, v83
	v_cvt_pk_bf16_f32 v185, v84, v85
	v_cvt_pk_bf16_f32 v186, v74, v75
	v_cvt_pk_bf16_f32 v187, v76, v77
	ds_bpermute_b32 v180, v162, v180
	ds_bpermute_b32 v181, v162, v181
	ds_bpermute_b32 v182, v162, v182
	ds_bpermute_b32 v183, v162, v183
	ds_bpermute_b32 v184, v162, v184
	ds_bpermute_b32 v185, v162, v185
	ds_bpermute_b32 v186, v162, v186
	ds_bpermute_b32 v187, v162, v187
	v_add_u32_e32 v200, 32, v149
	v_mad_i64_i32 v[196:197], s[4:5], v200, s11, v[140:141]
	v_lshl_add_u64 v[196:197], v[196:197], 0, v[142:143]
	s_waitcnt lgkmcnt(8)
	global_store_dwordx4 v[198:199], v[188:191], off nt
	global_store_dwordx4 v[198:199], v[192:195], off offset:256 nt
	v_pk_mul_f32 v[86:87], v[86:87], v[170:171] op_sel_hi:[1,0]
	v_pk_mul_f32 v[88:89], v[88:89], v[170:171] op_sel_hi:[1,0]
	v_pk_mul_f32 v[78:79], v[78:79], v[170:171] op_sel_hi:[1,0]
	v_pk_mul_f32 v[80:81], v[80:81], v[170:171] op_sel_hi:[1,0]
	v_cvt_pk_bf16_f32 v188, v86, v87
	v_cvt_pk_bf16_f32 v189, v88, v89
	v_cvt_pk_bf16_f32 v190, v78, v79
	v_cvt_pk_bf16_f32 v191, v80, v81
	v_pk_mul_f32 v[70:71], v[70:71], v[170:171] op_sel_hi:[1,0]
	v_pk_mul_f32 v[72:73], v[72:73], v[170:171] op_sel_hi:[1,0]
	v_pk_mul_f32 v[66:67], v[66:67], v[170:171] op_sel_hi:[1,0]
	v_pk_mul_f32 v[68:69], v[68:69], v[170:171] op_sel_hi:[1,0]
	v_cvt_pk_bf16_f32 v192, v70, v71
	v_cvt_pk_bf16_f32 v193, v72, v73
	v_cvt_pk_bf16_f32 v194, v66, v67
	v_cvt_pk_bf16_f32 v195, v68, v69
	ds_bpermute_b32 v188, v162, v188
	ds_bpermute_b32 v189, v162, v189
	ds_bpermute_b32 v190, v162, v190
	ds_bpermute_b32 v191, v162, v191
	ds_bpermute_b32 v192, v162, v192
	ds_bpermute_b32 v193, v162, v193
	ds_bpermute_b32 v194, v162, v194
	ds_bpermute_b32 v195, v162, v195
	v_add_u32_e32 v200, 48, v149
	v_mad_i64_i32 v[198:199], s[4:5], v200, s11, v[140:141]
	v_lshl_add_u64 v[198:199], v[198:199], 0, v[142:143]
	s_waitcnt lgkmcnt(8)
	global_store_dwordx4 v[196:197], v[180:183], off nt
	global_store_dwordx4 v[196:197], v[184:187], off offset:256 nt
	v_pk_mul_f32 v[62:63], v[62:63], v[172:173] op_sel_hi:[1,0]
	v_pk_mul_f32 v[64:65], v[64:65], v[172:173] op_sel_hi:[1,0]
	v_pk_mul_f32 v[58:59], v[58:59], v[172:173] op_sel_hi:[1,0]
	v_pk_mul_f32 v[60:61], v[60:61], v[172:173] op_sel_hi:[1,0]
	v_cvt_pk_bf16_f32 v180, v62, v63
	v_cvt_pk_bf16_f32 v181, v64, v65
	v_cvt_pk_bf16_f32 v182, v58, v59
	v_cvt_pk_bf16_f32 v183, v60, v61
	v_pk_mul_f32 v[50:51], v[50:51], v[172:173] op_sel_hi:[1,0]
	v_pk_mul_f32 v[52:53], v[52:53], v[172:173] op_sel_hi:[1,0]
	v_pk_mul_f32 v[42:43], v[42:43], v[172:173] op_sel_hi:[1,0]
	v_pk_mul_f32 v[44:45], v[44:45], v[172:173] op_sel_hi:[1,0]
	v_cvt_pk_bf16_f32 v184, v50, v51
	v_cvt_pk_bf16_f32 v185, v52, v53
	v_cvt_pk_bf16_f32 v186, v42, v43
	v_cvt_pk_bf16_f32 v187, v44, v45
	ds_bpermute_b32 v180, v162, v180
	ds_bpermute_b32 v181, v162, v181
	ds_bpermute_b32 v182, v162, v182
	ds_bpermute_b32 v183, v162, v183
	ds_bpermute_b32 v184, v162, v184
	ds_bpermute_b32 v185, v162, v185
	ds_bpermute_b32 v186, v162, v186
	ds_bpermute_b32 v187, v162, v187
	v_add_u32_e32 v200, 128, v149
	v_mad_i64_i32 v[196:197], s[4:5], v200, s11, v[140:141]
	v_lshl_add_u64 v[196:197], v[196:197], 0, v[142:143]
	s_waitcnt lgkmcnt(8)
	global_store_dwordx4 v[198:199], v[188:191], off nt
	global_store_dwordx4 v[198:199], v[192:195], off offset:256 nt
	v_pk_mul_f32 v[54:55], v[54:55], v[174:175] op_sel_hi:[1,0]
	v_pk_mul_f32 v[56:57], v[56:57], v[174:175] op_sel_hi:[1,0]
	v_pk_mul_f32 v[46:47], v[46:47], v[174:175] op_sel_hi:[1,0]
	v_pk_mul_f32 v[48:49], v[48:49], v[174:175] op_sel_hi:[1,0]
	v_cvt_pk_bf16_f32 v188, v54, v55
	v_cvt_pk_bf16_f32 v189, v56, v57
	v_cvt_pk_bf16_f32 v190, v46, v47
	v_cvt_pk_bf16_f32 v191, v48, v49
	v_pk_mul_f32 v[34:35], v[34:35], v[174:175] op_sel_hi:[1,0]
	v_pk_mul_f32 v[36:37], v[36:37], v[174:175] op_sel_hi:[1,0]
	v_pk_mul_f32 v[26:27], v[26:27], v[174:175] op_sel_hi:[1,0]
	v_pk_mul_f32 v[28:29], v[28:29], v[174:175] op_sel_hi:[1,0]
	v_cvt_pk_bf16_f32 v192, v34, v35
	v_cvt_pk_bf16_f32 v193, v36, v37
	v_cvt_pk_bf16_f32 v194, v26, v27
	v_cvt_pk_bf16_f32 v195, v28, v29
	ds_bpermute_b32 v188, v162, v188
	ds_bpermute_b32 v189, v162, v189
	ds_bpermute_b32 v190, v162, v190
	ds_bpermute_b32 v191, v162, v191
	ds_bpermute_b32 v192, v162, v192
	ds_bpermute_b32 v193, v162, v193
	ds_bpermute_b32 v194, v162, v194
	ds_bpermute_b32 v195, v162, v195
	v_add_u32_e32 v200, 144, v149
	v_mad_i64_i32 v[198:199], s[4:5], v200, s11, v[140:141]
	v_lshl_add_u64 v[198:199], v[198:199], 0, v[142:143]
	s_waitcnt lgkmcnt(8)
	global_store_dwordx4 v[196:197], v[180:183], off nt
	global_store_dwordx4 v[196:197], v[184:187], off offset:256 nt
	v_pk_mul_f32 v[38:39], v[38:39], v[176:177] op_sel_hi:[1,0]
	v_pk_mul_f32 v[40:41], v[40:41], v[176:177] op_sel_hi:[1,0]
	v_pk_mul_f32 v[30:31], v[30:31], v[176:177] op_sel_hi:[1,0]
	v_pk_mul_f32 v[32:33], v[32:33], v[176:177] op_sel_hi:[1,0]
	v_cvt_pk_bf16_f32 v180, v38, v39
	v_cvt_pk_bf16_f32 v181, v40, v41
	v_cvt_pk_bf16_f32 v182, v30, v31
	v_cvt_pk_bf16_f32 v183, v32, v33
	v_pk_mul_f32 v[18:19], v[18:19], v[176:177] op_sel_hi:[1,0]
	v_pk_mul_f32 v[20:21], v[20:21], v[176:177] op_sel_hi:[1,0]
	v_pk_mul_f32 v[10:11], v[10:11], v[176:177] op_sel_hi:[1,0]
	v_pk_mul_f32 v[12:13], v[12:13], v[176:177] op_sel_hi:[1,0]
	v_cvt_pk_bf16_f32 v184, v18, v19
	v_cvt_pk_bf16_f32 v185, v20, v21
	v_cvt_pk_bf16_f32 v186, v10, v11
	v_cvt_pk_bf16_f32 v187, v12, v13
	ds_bpermute_b32 v180, v162, v180
	ds_bpermute_b32 v181, v162, v181
	ds_bpermute_b32 v182, v162, v182
	ds_bpermute_b32 v183, v162, v183
	ds_bpermute_b32 v184, v162, v184
	ds_bpermute_b32 v185, v162, v185
	ds_bpermute_b32 v186, v162, v186
	ds_bpermute_b32 v187, v162, v187
	v_add_u32_e32 v200, 160, v149
	v_mad_i64_i32 v[196:197], s[4:5], v200, s11, v[140:141]
	v_lshl_add_u64 v[196:197], v[196:197], 0, v[142:143]
	s_waitcnt lgkmcnt(8)
	global_store_dwordx4 v[198:199], v[188:191], off nt
	global_store_dwordx4 v[198:199], v[192:195], off offset:256 nt
	v_pk_mul_f32 v[22:23], v[22:23], v[178:179] op_sel_hi:[1,0]
	v_pk_mul_f32 v[24:25], v[24:25], v[178:179] op_sel_hi:[1,0]
	v_pk_mul_f32 v[14:15], v[14:15], v[178:179] op_sel_hi:[1,0]
	v_pk_mul_f32 v[16:17], v[16:17], v[178:179] op_sel_hi:[1,0]
	v_cvt_pk_bf16_f32 v188, v22, v23
	v_cvt_pk_bf16_f32 v189, v24, v25
	v_cvt_pk_bf16_f32 v190, v14, v15
	v_cvt_pk_bf16_f32 v191, v16, v17
	v_pk_mul_f32 v[6:7], v[6:7], v[178:179] op_sel_hi:[1,0]
	v_pk_mul_f32 v[8:9], v[8:9], v[178:179] op_sel_hi:[1,0]
	v_pk_mul_f32 v[2:3], v[2:3], v[178:179] op_sel_hi:[1,0]
	v_pk_mul_f32 v[4:5], v[4:5], v[178:179] op_sel_hi:[1,0]
	v_cvt_pk_bf16_f32 v192, v6, v7
	v_cvt_pk_bf16_f32 v193, v8, v9
	v_cvt_pk_bf16_f32 v194, v2, v3
	v_cvt_pk_bf16_f32 v195, v4, v5
	ds_bpermute_b32 v188, v162, v188
	ds_bpermute_b32 v189, v162, v189
	ds_bpermute_b32 v190, v162, v190
	ds_bpermute_b32 v191, v162, v191
	ds_bpermute_b32 v192, v162, v192
	ds_bpermute_b32 v193, v162, v193
	ds_bpermute_b32 v194, v162, v194
	ds_bpermute_b32 v195, v162, v195
	v_add_u32_e32 v200, 176, v149
	v_mad_i64_i32 v[198:199], s[4:5], v200, s11, v[140:141]
	v_lshl_add_u64 v[198:199], v[198:199], 0, v[142:143]
	s_waitcnt lgkmcnt(8)
	global_store_dwordx4 v[196:197], v[180:183], off nt
	global_store_dwordx4 v[196:197], v[184:187], off offset:256 nt
	s_waitcnt lgkmcnt(0)
	global_store_dwordx4 v[198:199], v[188:191], off nt
	global_store_dwordx4 v[198:199], v[192:195], off offset:256 nt
	s_cbranch_vccnz .LBB0_485
	s_andn2_b64 vcc, exec, s[14:15]
	s_cbranch_vccnz .LBB0_484
	s_barrier
	s_branch .LBB0_484
